# v27 + static wave priority skew in attention units: waves 0-3 run at s_setprio 2, waves 4-7 at 0, so the two waves of a SIMD fall out of lockstep
# speedup vs baseline: 1.0031x; 1.0031x over previous
.LBB0_950:
	v_readfirstlane_b32 s22, v0
	s_cmpk_lt_u32 s22, 0x100
	s_cbranch_scc0 .Lprio_skip_b_lat
	s_setprio 2

.LBB0_961:
	v_readfirstlane_b32 s4, v0
	s_cmpk_lt_u32 s4, 0x100
	s_cbranch_scc0 .Lprio_skip_b_ctx
	s_setprio 2

.LBB0_1012:
	v_readfirstlane_b32 s16, v0
	s_cmpk_lt_u32 s16, 0x100
	s_cbranch_scc0 .Lprio_skip_a_lat
	s_setprio 2
